# ssd-dpp-scan
# baseline (speedup 1.0000x reference)
; __device__ __forceinline__ void ssd_item(const Params& p, LAS unsigned char* lds, int b, int head, bool sample) {
;     ...
;         const float dtl = P.dt;
;         float cs = dtl * a_h;
; #pragma unroll
;         for (int o = 1; o < 64; o <<= 1) { const float t = __shfl_up(cs, o); if (lane >= o) cs += t; }
;         const float cs_last = __shfl(cs, 63);
;         const float wl = dtl * __expf(cs_last - cs);
;         if (wave == 0) { acs[lane] = cs; dtv[lane] = dtl; }
.LBB0_1249:
	s_waitcnt vmcnt(0)
	v_mul_f32_e64 v2, v1, -v77
	s_andn2_b64 vcc, exec, s[86:87]
	s_nop 1
	v_add_f32_dpp v2, v2, v2 row_shr:1 row_mask:0xf bank_mask:0xf bound_ctrl:0
	s_nop 1
	v_add_f32_dpp v2, v2, v2 row_shr:2 row_mask:0xf bank_mask:0xf bound_ctrl:0
	s_nop 1
	v_add_f32_dpp v2, v2, v2 row_shr:4 row_mask:0xf bank_mask:0xf bound_ctrl:0
	s_nop 1
	v_add_f32_dpp v2, v2, v2 row_shr:8 row_mask:0xf bank_mask:0xf bound_ctrl:0
	s_nop 1
	v_add_f32_dpp v2, v2, v2 row_bcast:15 row_mask:0xa bank_mask:0xf
	s_nop 1
	v_add_f32_dpp v2, v2, v2 row_bcast:31 row_mask:0xc bank_mask:0xf
	ds_bpermute_b32 v166, v106, v2
	s_cbranch_vccnz .LBB0_1251
	ds_write_b32 v108, v2
	ds_write_b32 v107, v1
